# layer-0 SSM: waves 4,5 take all sample items so the four conversion waves start converting at once; on top of the v54 stack
# speedup vs baseline: 1.0016x; 1.0016x over previous
; #define LAS __attribute__((address_space(3)))
; template <bool FULL>
; __device__ __forceinline__ void ssm_core(const Args& a, LAS unsigned char* wl, int j, int L, bool samp, int n, int g, int tb, int te, float& hr, float& hi, int lane) {
;     unsigned char* ws = a.ws;
;     const size_t rowbase = samp ? (size_t)MP + (size_t)n * DSEQ : (size_t)n * SEQ;
;     const float* xbase = (L == 0) ? (samp ? a.in[1] + (size_t)n * DSEQ * D : a.in[0] + rowbase * D) : (const float*)(ws + WS_X) + rowbase * D;
;     const int G4 = lane >> 4, c = lane & 15;
;     const bf16x8* bfp = (const bf16x8*)(ws + WS_PAR + PAR_BFRAG) + (size_t)(j * NG + g) * 8 * 64 + lane;
;     const bf16x8* cfp = (const bf16x8*)(ws + WS_PAR + PAR_CFRAG) + (size_t)(j * NG + g) * 4 * 64 + lane;
;     bf16x8 Bf[8], Cf[4];
; #pragma unroll
;     for (int i = 0; i < 8; ++i) Bf[i] = bfp[i * 64];
;     if (FULL) {
; #pragma unroll
;         for (int i = 0; i < 4; ++i) Cf[i] = cfp[i * 64]; }
;     const float* ab = (const float*)(ws + WS_PAR + PAR_ABAR) + ((size_t)(j * NG + g) * NP + lane) * 2; const float ar = ab[0], ai = ab[1];
;     const float dsk = a.in[14][(size_t)j * D + g * NQ + c];
;     LAS float* BUs = (LAS float*)wl; LAS float* Us = (LAS float*)(wl + 16 * SSM_BUS * 4);
;     bf16_t* Y = (bf16_t*)(ws + WS_Y);
;     const float* up = xbase + (size_t)c * D + g * NQ + 8 * (G4 & 1);
;     auto ldu = [&](int trow, f32x4& lo, f32x4& hi4) { const float* p = up + (size_t)trow * D; lo = *(const f32x4*)p; hi4 = *(const f32x4*)(p + 4); };
; template <bool CONV> __device__ __forceinline__ void ph_ssm(const Args& a, LAS unsigned char* lds, int j, int L, int nblk, int b) {
;     const int tid = tid_fresh(); const int wave = __builtin_amdgcn_readfirstlane(tid >> 6), lane = tid & 63;
;     LAS unsigned char* wl = CONV ? (wave < 2 ? lds + wave * SSM_WLDS : lds + 2 * SSM_WLDS + (wave - 2) * CONV_LDS) : lds + wave * SSM_WLDS;
;     if (wave < 2) { for (int it = b * 2 + wave; it < NB * NG; it += nblk * 2) ssm_item(a, wl, j, L, false, it / NG, it % NG, lane); }
;     else { for (int it = b * 6 + (wave - 2); it < DB * NG; it += nblk * 6) ssm_item(a, wl, j, L, true, it / NG, it % NG, lane);
;         if (CONV && (wave & 2)) conv_worker(a, (LAS float*)wl, b * 4 + (wave & 1) + ((wave >> 2) << 1), nblk * 4, lane); }
; }
.LBB0_117:
	s_or_b64 exec, exec, s[2:3]
	s_waitcnt lgkmcnt(0)
	v_mov_b32_e32 v1, v0
	s_barrier
	s_add_i32 s0, 0, 0xffffe000
	v_readfirstlane_b32 s26, v1
	s_ashr_i32 s39, s26, 6
	s_cmp_lt_i32 s39, 2
	s_movk_i32 s1, 0x3100
	s_cselect_b32 s1, s1, 0x4100
	s_cselect_b32 s0, 0, s0
	s_mul_i32 s1, s1, s39
	s_add_i32 s33, s0, s1
	v_and_b32_e32 v130, 63, v1
	s_cmp_gt_i32 s39, 1
	s_mov_b64 s[2:3], -1
	s_cbranch_scc0 .LBB0_278
	s_mul_i32 s2, s90, 2
	s_add_i32 s2, s2, s39
	s_add_i32 s27, s2, -4
	s_and_b32 s2, s39, 6
	s_cmp_eq_u32 s2, 4
	s_cselect_b32 s27, s27, 0x1000
	s_cmpk_gt_i32 s27, 0xfff
	s_cbranch_scc1 .LBB0_123
	v_and_b32_e32 v64, 15, v1
	v_mov_b32_e32 v7, s33
	s_movk_i32 s2, 0x210
	v_mad_u32_u24 v14, v64, s2, v7
	s_load_dwordx4 s[12:15], s[86:87], 0xf0
	s_load_dwordx4 s[8:11], s[86:87], 0x8
	s_load_dwordx2 s[2:3], s[86:87], 0x18
	v_mov_b32_e32 v63, 0
	v_lshrrev_b32_e32 v5, 4, v130
	v_lshlrev_b32_e32 v2, 13, v64
	v_mov_b32_e32 v3, v63
	v_mul_u32_u24_e32 v13, 0x210, v64
	v_mul_i32_i24_e32 v16, 0xfffffdf4, v64
	s_waitcnt lgkmcnt(0)
	v_lshl_add_u64 v[74:75], s[8:9], 0, v[2:3]
	v_add3_u32 v2, v13, v16, s1
	v_lshlrev_b32_e32 v3, 8, v5
	v_lshlrev_b32_e32 v11, 6, v64
	v_lshlrev_b32_e32 v15, 5, v5
	s_load_dwordx2 s[4:5], s[86:87], 0x70
	v_add3_u32 v2, v2, v3, s0
	v_lshlrev_b32_e32 v8, 4, v130
	v_mov_b32_e32 v9, v63
	v_add_u32_e32 v90, 0x2100, v2
	v_add_u32_e32 v2, s1, v11
	v_and_b32_e32 v3, 32, v15
	v_lshrrev_b32_e32 v4, 1, v130
	v_lshl_add_u64 v[8:9], s[14:15], 0, v[8:9]
	s_mov_b64 s[6:7], 0x2fb22000
	s_add_u32 s8, s12, 0x7480000
	v_add3_u32 v2, v2, v3, s0
	v_lshlrev_b32_e32 v62, 3, v130
	v_and_b32_e32 v4, 8, v4
	v_lshlrev_b32_e32 v6, 2, v64
	v_lshl_add_u64 v[66:67], v[8:9], 0, s[6:7]
	s_mov_b64 s[6:7], 0x2fd22000
	s_addc_u32 s9, s13, 0
	v_add_u32_e32 v91, 0x2100, v2
	v_lshlrev_b32_e32 v2, 10, v1
	v_lshl_add_u32 v10, v4, 2, s33
	v_add_u32_e32 v12, s33, v6
	v_mul_u32_u24_e32 v17, 0x840, v5
	v_lshl_add_u64 v[68:69], v[8:9], 0, s[6:7]
	v_lshl_add_u64 v[8:9], s[14:15], 0, v[62:63]
	s_mov_b64 s[6:7], 0x2f900000
	v_mov_b32_e32 v7, v63
	s_add_u32 s16, s12, 0x7680000
	v_and_b32_e32 v62, 0xc000, v2
	s_mov_b32 s12, 0
	v_cmp_gt_u32_e32 vcc, 32, v130
	v_lshl_add_u32 v65, v130, 2, s33
	s_mul_i32 s28, s89, 2
	v_lshl_add_u64 v[70:71], v[8:9], 0, s[6:7]
	s_waitcnt lgkmcnt(0)
	v_lshl_add_u64 v[72:73], s[4:5], 0, v[6:7]
	s_addc_u32 s17, s13, 0
	v_lshl_add_u64 v[76:77], s[14:15], 0, v[62:63]
	s_movk_i32 s29, 0x1000
	v_lshlrev_b32_e32 v62, 2, v4
	s_mov_b64 s[18:19], 0x60000
	s_mov_b32 s30, 0x60000
	s_mov_b64 s[20:21], 0x40000
	s_mov_b32 s31, 0x40000
	s_mov_b64 s[22:23], 0x20000
	s_mov_b32 s34, 0x20000
	v_add_u32_e32 v92, v10, v11
	s_mov_b32 s13, s12
	s_mov_b32 s14, s12
	s_mov_b32 s15, s12
	v_add_u32_e32 v93, v12, v17
	v_add_u32_e32 v94, v14, v15
	s_movk_i32 s35, 0x7fff
	s_mov_b32 s36, 0x2f101000
	s_mov_b32 s37, 0x2f103000
